# top-k: next item's key fragments and Q tile prefetched during the current item's sort, counted vmcnt so the loop top does not wait on the previous item's stores
# baseline (speedup 1.0000x reference)
; DI void phase_topk(const Params& p, int l, int bid, int nblk, char* smem) {
;     ...
;   const int nitem = (l == 1 ? NB * 32 : ROWS / 64) * 16;
;   for (int it = bid; it < nitem; it += nblk) {
;     const int hh = it & 15, ri = it >> 4;
;     const int rt = (l == 1) ? (ri >> 5) * 36 + 4 + (ri & 31) : ri;
;     const int row0 = rt * 64;
;     const u16* kb = WSP(const u16, OFF_K12) + (size_t)(l * 2 + (hh & 1)) * 16384;
;     bf16x8 kfr[8];
; #pragma unroll
;     for (int ks = 0; ks < 8; ++ks) kfr[ks] = *(const bf16x8*)&kb[(w * 32 + l32) * 128 + ks * 16 + h * 8];
;     __builtin_amdgcn_sched_barrier(0);
; #pragma unroll
;     for (int i = 0; i < 4; ++i) {
;       const int q = tid + 256 * i, r = q >> 4, ch = q & 15;
;       *(uint4*)&qs[r * 136 + ch * 8] = *(const uint4*)&Q[(size_t)(row0 + r) * 2048 + hh * 128 + ch * 8];
;     }
.LBB0_1445:
	s_or_b64 exec, exec, s[0:1]
	v_readlane_b32 s0, v254, 8
	v_readlane_b32 s1, v254, 9
	s_and_b64 s[0:1], s[0:1], exec
	s_movk_i32 s0, 0x2400
	s_cselect_b32 s13, s0, 0x2000
	v_readlane_b32 s0, v253, 0
	s_cmp_ge_i32 s0, s13
	s_waitcnt lgkmcnt(0)
	v_mov_b32_e32 v0, v218
	s_barrier
	s_cbranch_scc1 .LBB0_1453
	v_and_b32_e32 v1, 31, v0
	v_bfe_u32 v7, v0, 5, 1
	v_ashrrev_i32_e32 v3, 6, v0
	v_lshlrev_b32_e32 v4, 12, v3
	v_lshlrev_b32_e32 v5, 7, v1
	v_lshlrev_b32_e32 v6, 3, v7
	v_or3_b32 v4, v4, v5, v6
	v_lshlrev_b32_e32 v5, 4, v0
	v_lshl_add_u32 v2, v1, 2, 0
	v_and_b32_e32 v172, 0xf0, v5
	v_mul_u32_u24_e32 v1, 0x10c, v1
	v_lshlrev_b32_e32 v5, 4, v7
	s_movk_i32 s0, 0x84
	v_add3_u32 v44, v2, v1, v5
	v_mad_u64_u32 v[2:3], s[0:1], v3, s0, v[2:3]
	v_add_u32_e32 v6, 0, v172
	v_ashrrev_i32_e32 v45, 2, v0
	v_and_b32_e32 v1, 3, v0
	s_movk_i32 s0, 0x214
	v_ashrrev_i32_e32 v47, 4, v0
	v_mul_lo_u32 v3, v45, s0
	v_mul_u32_u24_e32 v8, 0x84, v1
	v_lshlrev_b32_e32 v46, 5, v1
	v_cmp_eq_u32_e64 s[0:1], 0, v1
	v_mad_u64_u32 v[34:35], s[34:35], v47, s52, v[6:7]
	v_add_u32_e32 v1, 0x100, v0
	v_ashrrev_i32_e32 v35, 4, v1
	v_mad_u64_u32 v[36:37], s[34:35], v35, s52, v[6:7]
	v_add_u32_e32 v1, 0x200, v0
	v_ashrrev_i32_e32 v37, 4, v1
	v_mad_u64_u32 v[38:39], s[34:35], v37, s52, v[6:7]
	v_add_u32_e32 v0, 0x300, v0
	v_ashrrev_i32_e32 v39, 4, v0
	v_readlane_b32 s16, v254, 51
	v_add_u32_e32 v3, 0, v3
	v_ashrrev_i32_e32 v5, 31, v4
	v_mad_u64_u32 v[40:41], s[34:35], v39, s52, v[6:7]
	v_mul_u32_u24_e32 v0, 0x850, v7
	v_readlane_b32 s17, v254, 52
	s_lshl_b32 s36, s24, 15
	v_lshl_add_u64 v[32:33], s[96:97], 0, v[172:173]
	v_lshl_add_u64 v[42:43], v[4:5], 1, s[16:17]
	v_add_u32_e32 v41, v2, v0
	v_add_u32_e32 v48, v3, v8
	v_readlane_b32 s37, v255, 60
	v_readlane_b32 s38, v253, 0
	s_cmp_lg_u64 s[62:63], 0
	s_cbranch_scc0 .Ltk_pf_l0_2
	s_ashr_i32 s46, s38, 9
	s_mul_i32 s46, s46, 36
	s_bfe_u32 s47, s38, 0x50004
	s_add_i32 s46, s46, s47
	s_add_i32 s46, s46, 4
	s_branch .Ltk_pf_go_2
.Ltk_pf_l0_2:
	s_ashr_i32 s46, s38, 4
.Ltk_pf_go_2:
	s_lshl_b32 s46, s46, 6
	s_and_b32 s47, s38, 1
	s_lshl_b32 s47, s47, 14
	s_or_b32 s47, s47, s36
	s_lshl_b32 s48, s47, 1
	s_mov_b32 s49, 0
	v_lshl_add_u64 v[148:149], v[42:43], 0, s[48:49]
	global_load_dwordx4 v[100:103], v[148:149], off
	global_load_dwordx4 v[104:107], v[148:149], off offset:32
	global_load_dwordx4 v[108:111], v[148:149], off offset:64
	global_load_dwordx4 v[112:115], v[148:149], off offset:96
	global_load_dwordx4 v[116:119], v[148:149], off offset:128
	global_load_dwordx4 v[120:123], v[148:149], off offset:160
	global_load_dwordx4 v[124:127], v[148:149], off offset:192
	global_load_dwordx4 v[128:131], v[148:149], off offset:224
	s_and_b32 s47, s38, 15
	s_lshl_b32 s48, s47, 8
	v_lshl_add_u64 v[150:151], v[32:33], 0, s[48:49]
	v_add_u32_e32 v152, s46, v47
	v_ashrrev_i32_e32 v153, 31, v152
	v_lshlrev_b64 v[152:153], 12, v[152:153]
	v_lshl_add_u64 v[152:153], v[150:151], 0, v[152:153]
	global_load_dwordx4 v[132:135], v[152:153], off
	v_add_u32_e32 v152, s46, v35
	v_ashrrev_i32_e32 v153, 31, v152
	v_lshlrev_b64 v[152:153], 12, v[152:153]
	v_lshl_add_u64 v[152:153], v[150:151], 0, v[152:153]
	global_load_dwordx4 v[136:139], v[152:153], off
	v_add_u32_e32 v152, s46, v37
	v_ashrrev_i32_e32 v153, 31, v152
	v_lshlrev_b64 v[152:153], 12, v[152:153]
	v_lshl_add_u64 v[152:153], v[150:151], 0, v[152:153]
	global_load_dwordx4 v[140:143], v[152:153], off
	v_add_u32_e32 v152, s46, v39
	v_ashrrev_i32_e32 v153, 31, v152
	v_lshlrev_b64 v[152:153], 12, v[152:153]
	v_lshl_add_u64 v[152:153], v[150:151], 0, v[152:153]
	global_load_dwordx4 v[144:147], v[152:153], off
	s_waitcnt vmcnt(0)
	s_branch .LBB0_1448

; DI void phase_topk(const Params& p, int l, int bid, int nblk, char* smem) {
;     ...
;     bf16x8 kfr[8];
; #pragma unroll
;     for (int ks = 0; ks < 8; ++ks) kfr[ks] = *(const bf16x8*)&kb[(w * 32 + l32) * 128 + ks * 16 + h * 8];
;     __builtin_amdgcn_sched_barrier(0);
; #pragma unroll
;     for (int i = 0; i < 4; ++i) {
;       const int q = tid + 256 * i, r = q >> 4, ch = q & 15;
;       *(uint4*)&qs[r * 136 + ch * 8] = *(const uint4*)&Q[(size_t)(row0 + r) * 2048 + hh * 128 + ch * 8];
;     }
;     __syncthreads();
;     f32x16 acc[2];
; #pragma unroll
;     for (int i = 0; i < 2; ++i)
; #pragma unroll
;       for (int r = 0; r < 16; ++r) acc[i][r] = 0.f;
; #pragma unroll
;     for (int ks = 0; ks < 8; ++ks) {
;       const bf16x8 bq = kfr[ks];
;       const bf16x8 a0 = *(const bf16x8*)&qs[(l32) * 136 + ks * 16 + h * 8];
;       const bf16x8 a1 = *(const bf16x8*)&qs[(32 + l32) * 136 + ks * 16 + h * 8];
;       acc[0] = __builtin_amdgcn_mfma_f32_32x32x16_bf16(a0, bq, acc[0], 0, 0, 0);
;       acc[1] = __builtin_amdgcn_mfma_f32_32x32x16_bf16(a1, bq, acc[1], 0, 0, 0);
;     }
; #pragma unroll
;     for (int mt = 0; mt < 2; ++mt)
; #pragma unroll
;       for (int i = 0; i < 16; ++i) {
;         const int r = mt * 32 + (i & 3) + 8 * (i >> 2) + 4 * h;
;         sc[r * 133 + w * 33 + l32] = acc[mt][i];
;       }
;     __syncthreads();
.LBB0_1451:
	s_and_b32 s35, s37, 0x4000
	s_or_b32 s35, s35, s36
	s_lshl_b32 s86, s35, 1
	s_and_b32 s39, s38, 15
	s_lshl_b32 s40, s34, 6
	s_waitcnt vmcnt(8)
	v_mov_b64_e32 v[0:1], v[100:101]
	v_mov_b64_e32 v[2:3], v[102:103]
	v_mov_b64_e32 v[50:51], v[104:105]
	v_mov_b64_e32 v[52:53], v[106:107]
	v_mov_b64_e32 v[54:55], v[108:109]
	v_mov_b64_e32 v[56:57], v[110:111]
	v_mov_b64_e32 v[58:59], v[112:113]
	v_mov_b64_e32 v[60:61], v[114:115]
	v_mov_b64_e32 v[62:63], v[116:117]
	v_mov_b64_e32 v[64:65], v[118:119]
	v_mov_b64_e32 v[66:67], v[120:121]
	v_mov_b64_e32 v[68:69], v[122:123]
	v_mov_b64_e32 v[70:71], v[124:125]
	v_mov_b64_e32 v[72:73], v[126:127]
	v_mov_b64_e32 v[74:75], v[128:129]
	v_mov_b64_e32 v[76:77], v[130:131]
	ds_write_b128 v34, v[132:135]
	ds_write_b128 v36, v[136:139]
	ds_write_b128 v38, v[140:143]
	ds_write_b128 v40, v[144:147]
	v_add_u32_e32 v49, 0x4400, v41
	s_add_i32 s50, s38, s54
	s_cmp_lt_i32 s50, s13
	s_cbranch_scc0 .Ltk_nopf
	s_cmp_lg_u64 s[62:63], 0
	s_cbranch_scc0 .Ltk_pf_l0_1
	s_ashr_i32 s46, s50, 9
	s_mul_i32 s46, s46, 36
	s_bfe_u32 s47, s50, 0x50004
	s_add_i32 s46, s46, s47
	s_add_i32 s46, s46, 4
	s_branch .Ltk_pf_go_1
.Ltk_pf_l0_1:
	s_ashr_i32 s46, s50, 4
.Ltk_pf_go_1:
	s_lshl_b32 s46, s46, 6
	s_and_b32 s47, s50, 1
	s_lshl_b32 s47, s47, 14
	s_or_b32 s47, s47, s36
	s_lshl_b32 s48, s47, 1
	s_mov_b32 s49, 0
	v_lshl_add_u64 v[148:149], v[42:43], 0, s[48:49]
	global_load_dwordx4 v[100:103], v[148:149], off
	global_load_dwordx4 v[104:107], v[148:149], off offset:32
	global_load_dwordx4 v[108:111], v[148:149], off offset:64
	global_load_dwordx4 v[112:115], v[148:149], off offset:96
	global_load_dwordx4 v[116:119], v[148:149], off offset:128
	global_load_dwordx4 v[120:123], v[148:149], off offset:160
	global_load_dwordx4 v[124:127], v[148:149], off offset:192
	global_load_dwordx4 v[128:131], v[148:149], off offset:224
	s_and_b32 s47, s50, 15
	s_lshl_b32 s48, s47, 8
	v_lshl_add_u64 v[150:151], v[32:33], 0, s[48:49]
	v_add_u32_e32 v152, s46, v47
	v_ashrrev_i32_e32 v153, 31, v152
	v_lshlrev_b64 v[152:153], 12, v[152:153]
	v_lshl_add_u64 v[152:153], v[150:151], 0, v[152:153]
	global_load_dwordx4 v[132:135], v[152:153], off
	v_add_u32_e32 v152, s46, v35
	v_ashrrev_i32_e32 v153, 31, v152
	v_lshlrev_b64 v[152:153], 12, v[152:153]
	v_lshl_add_u64 v[152:153], v[150:151], 0, v[152:153]
	global_load_dwordx4 v[136:139], v[152:153], off
	v_add_u32_e32 v152, s46, v37
	v_ashrrev_i32_e32 v153, 31, v152
	v_lshlrev_b64 v[152:153], 12, v[152:153]
	v_lshl_add_u64 v[152:153], v[150:151], 0, v[152:153]
	global_load_dwordx4 v[140:143], v[152:153], off
	v_add_u32_e32 v152, s46, v39
	v_ashrrev_i32_e32 v153, 31, v152
	v_lshlrev_b64 v[152:153], 12, v[152:153]
	v_lshl_add_u64 v[152:153], v[150:151], 0, v[152:153]
	global_load_dwordx4 v[144:147], v[152:153], off
.Ltk_nopf:
	s_movk_i32 s34, 0x7f
	s_waitcnt lgkmcnt(0)
	s_barrier
	ds_read_b128 v[4:7], v44 offset:8704
	ds_read_b128 v[8:11], v44
	ds_read_b128 v[78:81], v44 offset:32
	s_waitcnt lgkmcnt(1)
	v_mfma_f32_32x32x16_bf16 v[16:31], v[8:11], v[0:3], 0
	ds_read_b128 v[82:85], v44 offset:8736
	v_mfma_f32_32x32x16_bf16 v[0:15], v[4:7], v[0:3], 0
	s_waitcnt lgkmcnt(1)
	v_mfma_f32_32x32x16_bf16 v[16:31], v[78:81], v[50:53], v[16:31]
	s_waitcnt lgkmcnt(0)
	v_mfma_f32_32x32x16_bf16 v[0:15], v[82:85], v[50:53], v[0:15]
	ds_read_b128 v[50:53], v44 offset:64
	ds_read_b128 v[78:81], v44 offset:8768
	s_waitcnt lgkmcnt(1)
	v_mfma_f32_32x32x16_bf16 v[16:31], v[50:53], v[54:57], v[16:31]
	s_waitcnt lgkmcnt(0)
	v_mfma_f32_32x32x16_bf16 v[0:15], v[78:81], v[54:57], v[0:15]
	ds_read_b128 v[50:53], v44 offset:96
	ds_read_b128 v[54:57], v44 offset:8800
	s_waitcnt lgkmcnt(1)
	v_mfma_f32_32x32x16_bf16 v[16:31], v[50:53], v[58:61], v[16:31]
	s_waitcnt lgkmcnt(0)
	v_mfma_f32_32x32x16_bf16 v[0:15], v[54:57], v[58:61], v[0:15]
	ds_read_b128 v[50:53], v44 offset:128
	ds_read_b128 v[54:57], v44 offset:8832
	s_waitcnt lgkmcnt(1)
	v_mfma_f32_32x32x16_bf16 v[16:31], v[50:53], v[62:65], v[16:31]
	s_waitcnt lgkmcnt(0)
	v_mfma_f32_32x32x16_bf16 v[0:15], v[54:57], v[62:65], v[0:15]
	ds_read_b128 v[50:53], v44 offset:160
	ds_read_b128 v[54:57], v44 offset:8864
	s_waitcnt lgkmcnt(1)
	v_mfma_f32_32x32x16_bf16 v[16:31], v[50:53], v[66:69], v[16:31]
	s_waitcnt lgkmcnt(0)
	v_mfma_f32_32x32x16_bf16 v[0:15], v[54:57], v[66:69], v[0:15]
	ds_read_b128 v[50:53], v44 offset:192
	ds_read_b128 v[54:57], v44 offset:8896
	s_waitcnt lgkmcnt(1)
	v_mfma_f32_32x32x16_bf16 v[16:31], v[50:53], v[70:73], v[16:31]
	s_waitcnt lgkmcnt(0)
	v_mfma_f32_32x32x16_bf16 v[0:15], v[54:57], v[70:73], v[0:15]
	ds_read_b128 v[50:53], v44 offset:224
	ds_read_b128 v[54:57], v44 offset:8928
	s_waitcnt lgkmcnt(1)
	v_mfma_f32_32x32x16_bf16 v[16:31], v[50:53], v[74:77], v[16:31]
	s_waitcnt lgkmcnt(0)
	v_mfma_f32_32x32x16_bf16 v[0:15], v[54:57], v[74:77], v[0:15]
	s_nop 9
	ds_write2_b32 v49, v16, v17 offset1:133
	v_add_u32_e32 v16, 0x4800, v41
	ds_write2_b32 v16, v18, v19 offset0:10 offset1:143
	v_add_u32_e32 v16, 0x5400, v41
	ds_write2_b32 v16, v20, v21 offset0:40 offset1:173
	v_add_u32_e32 v16, 0x5800, v41
	ds_write2_b32 v16, v22, v23 offset0:50 offset1:183
	v_add_u32_e32 v16, 0x6400, v41
	ds_write2_b32 v16, v24, v25 offset0:80 offset1:213
	v_add_u32_e32 v16, 0x6800, v41
	ds_write2_b32 v16, v26, v27 offset0:90 offset1:223
	v_add_u32_e32 v16, 0x7400, v41
	ds_write2_b32 v16, v28, v29 offset0:120 offset1:253
	v_add_u32_e32 v16, 0x7a00, v41
	ds_write2_b32 v16, v30, v31 offset0:2 offset1:135
	v_add_u32_e32 v16, 0x8600, v41
	ds_write2_b32 v16, v0, v1 offset0:32 offset1:165
	v_add_u32_e32 v0, 0x8a00, v41
	ds_write2_b32 v0, v2, v3 offset0:42 offset1:175
	v_add_u32_e32 v0, 0x9600, v41
	ds_write2_b32 v0, v4, v5 offset0:72 offset1:205
	v_add_u32_e32 v0, 0x9a00, v41
	ds_write2_b32 v0, v6, v7 offset0:82 offset1:215
	v_add_u32_e32 v0, 0xa600, v41
	ds_write2_b32 v0, v8, v9 offset0:112 offset1:245
	v_add_u32_e32 v0, 0xaa00, v41
	ds_write2_b32 v0, v10, v11 offset0:122 offset1:255
	v_add_u32_e32 v0, 0xb800, v41
	ds_write2_b32 v0, v12, v13 offset0:24 offset1:157
	v_add_u32_e32 v0, 0xbc00, v41
	ds_write2_b32 v0, v14, v15 offset0:34 offset1:167
	v_add_u32_e32 v0, 0x4400, v48
	s_waitcnt lgkmcnt(0)
	s_barrier
; DI void phase_topk(const Params& p, int l, int bid, int nblk, char* smem) {
;     ...
;     {
;       const int r = tid >> 2, part = tid & 3;
;       u32 key[32];
; #pragma unroll
;       for (int j = 0; j < 32; ++j) {
;         const u32 u = __float_as_uint(sc[r * 133 + part * 33 + j]);
;         const u32 ord = (u & 0x80000000u) ? ~u : (u | 0x80000000u);
;         key[j] = (ord & ~127u) | (u32)(127 - (part * 32 + j));
;       }
	ds_read2_b32 v[0:1], v0 offset1:1
	s_waitcnt lgkmcnt(0)
	v_not_b32_e32 v2, v0
	v_cmp_gt_i32_e32 vcc, 0, v0
	s_nop 1
	v_cndmask_b32_e64 v0, -|v0|, v2, vcc
	v_and_b32_e32 v0, 0xffffff80, v0
	v_bitop3_b32 v2, v0, s34, v46 bitop3:0x36
	v_not_b32_e32 v0, v1
	v_cmp_gt_i32_e32 vcc, 0, v1
	s_nop 1
	v_cndmask_b32_e64 v0, -|v1|, v0, vcc
	v_and_b32_e32 v0, 0xffffff80, v0
	v_sub_u32_e32 v0, v0, v46
	v_add_u32_e32 v3, 0x7e, v0
	v_add_u32_e32 v0, 0x4408, v48
	ds_read2_b32 v[0:1], v0 offset1:1
	s_waitcnt lgkmcnt(0)
	v_not_b32_e32 v4, v0
	v_cmp_gt_i32_e32 vcc, 0, v0
	s_nop 1
	v_cndmask_b32_e64 v0, -|v0|, v4, vcc
	v_and_b32_e32 v0, 0xffffff80, v0
	v_sub_u32_e32 v0, v0, v46
	v_add_u32_e32 v4, 0x7d, v0
	v_not_b32_e32 v0, v1
	v_cmp_gt_i32_e32 vcc, 0, v1
	s_nop 1
	v_cndmask_b32_e64 v0, -|v1|, v0, vcc
	v_and_b32_e32 v0, 0xffffff80, v0
	v_sub_u32_e32 v0, v0, v46
	v_add_u32_e32 v5, 0x7c, v0
	v_add_u32_e32 v0, 0x4410, v48
	ds_read2_b32 v[0:1], v0 offset1:1
	s_waitcnt lgkmcnt(0)
	v_not_b32_e32 v6, v0
	v_cmp_gt_i32_e32 vcc, 0, v0
	s_nop 1
	v_cndmask_b32_e64 v0, -|v0|, v6, vcc
	v_and_b32_e32 v0, 0xffffff80, v0
	v_sub_u32_e32 v0, v0, v46
	v_add_u32_e32 v6, 0x7b, v0
	v_not_b32_e32 v0, v1
	v_cmp_gt_i32_e32 vcc, 0, v1
	s_nop 1
	v_cndmask_b32_e64 v0, -|v1|, v0, vcc
	v_and_b32_e32 v0, 0xffffff80, v0
	v_sub_u32_e32 v0, v0, v46
	v_add_u32_e32 v7, 0x7a, v0
	v_add_u32_e32 v0, 0x4418, v48
	ds_read2_b32 v[0:1], v0 offset1:1
	s_waitcnt lgkmcnt(0)
	v_not_b32_e32 v8, v0
	v_cmp_gt_i32_e32 vcc, 0, v0
	s_nop 1
	v_cndmask_b32_e64 v0, -|v0|, v8, vcc
	v_and_b32_e32 v0, 0xffffff80, v0
	v_sub_u32_e32 v0, v0, v46
	v_add_u32_e32 v8, 0x79, v0
	v_not_b32_e32 v0, v1
	v_cmp_gt_i32_e32 vcc, 0, v1
	s_nop 1
	v_cndmask_b32_e64 v0, -|v1|, v0, vcc
	v_and_b32_e32 v0, 0xffffff80, v0
	v_sub_u32_e32 v0, v0, v46
	v_add_u32_e32 v9, 0x78, v0
	v_add_u32_e32 v0, 0x4420, v48
	ds_read2_b32 v[0:1], v0 offset1:1
	s_waitcnt lgkmcnt(0)
	v_not_b32_e32 v10, v0
	v_cmp_gt_i32_e32 vcc, 0, v0
	s_nop 1
	v_cndmask_b32_e64 v0, -|v0|, v10, vcc
	v_and_b32_e32 v0, 0xffffff80, v0
	v_sub_u32_e32 v0, v0, v46
	v_add_u32_e32 v10, 0x77, v0
	v_not_b32_e32 v0, v1
	v_cmp_gt_i32_e32 vcc, 0, v1
	s_nop 1
	v_cndmask_b32_e64 v0, -|v1|, v0, vcc
	v_and_b32_e32 v0, 0xffffff80, v0
	v_sub_u32_e32 v0, v0, v46
	v_add_u32_e32 v11, 0x76, v0
	v_add_u32_e32 v0, 0x4428, v48
	ds_read2_b32 v[0:1], v0 offset1:1
	s_waitcnt lgkmcnt(0)
	v_not_b32_e32 v12, v0
	v_cmp_gt_i32_e32 vcc, 0, v0
	s_nop 1
	v_cndmask_b32_e64 v0, -|v0|, v12, vcc
	v_and_b32_e32 v0, 0xffffff80, v0
	v_sub_u32_e32 v0, v0, v46
	v_add_u32_e32 v12, 0x75, v0
	v_not_b32_e32 v0, v1
	v_cmp_gt_i32_e32 vcc, 0, v1
	s_nop 1
	v_cndmask_b32_e64 v0, -|v1|, v0, vcc
	v_and_b32_e32 v0, 0xffffff80, v0
	v_sub_u32_e32 v0, v0, v46
	v_add_u32_e32 v13, 0x74, v0
	v_add_u32_e32 v0, 0x4430, v48
	ds_read2_b32 v[0:1], v0 offset1:1
	s_waitcnt lgkmcnt(0)
	v_not_b32_e32 v14, v0
	v_cmp_gt_i32_e32 vcc, 0, v0
	s_nop 1
	v_cndmask_b32_e64 v0, -|v0|, v14, vcc
	v_and_b32_e32 v0, 0xffffff80, v0
	v_sub_u32_e32 v0, v0, v46
	v_add_u32_e32 v14, 0x73, v0
	v_not_b32_e32 v0, v1
	v_cmp_gt_i32_e32 vcc, 0, v1
	s_nop 1
	v_cndmask_b32_e64 v0, -|v1|, v0, vcc
	v_and_b32_e32 v0, 0xffffff80, v0
	v_sub_u32_e32 v0, v0, v46
	v_add_u32_e32 v15, 0x72, v0
	v_add_u32_e32 v0, 0x4438, v48
	ds_read2_b32 v[0:1], v0 offset1:1
	s_waitcnt lgkmcnt(0)
	v_not_b32_e32 v16, v0
	v_cmp_gt_i32_e32 vcc, 0, v0
	s_nop 1
	v_cndmask_b32_e64 v0, -|v0|, v16, vcc
	v_not_b32_e32 v16, v1
	v_cmp_gt_i32_e32 vcc, 0, v1
	v_and_b32_e32 v0, 0xffffff80, v0
	v_sub_u32_e32 v0, v0, v46
	v_cndmask_b32_e64 v1, -|v1|, v16, vcc
	v_add_u32_e32 v16, 0x4440, v48
	ds_read2_b32 v[16:17], v16 offset1:1
	v_and_b32_e32 v1, 0xffffff80, v1
	v_sub_u32_e32 v1, v1, v46
	v_add_u32_e32 v0, 0x71, v0
	v_add_u32_e32 v1, 0x70, v1
	s_waitcnt lgkmcnt(0)
	v_not_b32_e32 v18, v16
	v_cmp_gt_i32_e32 vcc, 0, v16
	s_nop 1
	v_cndmask_b32_e64 v16, -|v16|, v18, vcc
	v_not_b32_e32 v18, v17
	v_cmp_gt_i32_e32 vcc, 0, v17
	v_and_b32_e32 v16, 0xffffff80, v16
	v_sub_u32_e32 v16, v16, v46
	v_cndmask_b32_e64 v17, -|v17|, v18, vcc
	v_add_u32_e32 v18, 0x4448, v48
	ds_read2_b32 v[18:19], v18 offset1:1
	v_and_b32_e32 v17, 0xffffff80, v17
	v_sub_u32_e32 v17, v17, v46
	v_add_u32_e32 v16, 0x6f, v16
	v_add_u32_e32 v17, 0x6e, v17
	s_waitcnt lgkmcnt(0)
	v_not_b32_e32 v20, v18
	v_cmp_gt_i32_e32 vcc, 0, v18
	s_nop 1
	v_cndmask_b32_e64 v18, -|v18|, v20, vcc
	v_not_b32_e32 v20, v19
	v_cmp_gt_i32_e32 vcc, 0, v19
	v_and_b32_e32 v18, 0xffffff80, v18
	v_sub_u32_e32 v18, v18, v46
	v_cndmask_b32_e64 v19, -|v19|, v20, vcc
	v_add_u32_e32 v20, 0x4450, v48
	ds_read2_b32 v[20:21], v20 offset1:1
	v_and_b32_e32 v19, 0xffffff80, v19
	v_sub_u32_e32 v19, v19, v46
	v_add_u32_e32 v18, 0x6d, v18
	v_add_u32_e32 v19, 0x6c, v19
	s_waitcnt lgkmcnt(0)
	v_not_b32_e32 v22, v20
	v_cmp_gt_i32_e32 vcc, 0, v20
	s_nop 1
	v_cndmask_b32_e64 v20, -|v20|, v22, vcc
	v_not_b32_e32 v22, v21
	v_cmp_gt_i32_e32 vcc, 0, v21
	v_and_b32_e32 v20, 0xffffff80, v20
	v_sub_u32_e32 v20, v20, v46
	v_cndmask_b32_e64 v21, -|v21|, v22, vcc
	v_add_u32_e32 v22, 0x4458, v48
	ds_read2_b32 v[22:23], v22 offset1:1
	v_and_b32_e32 v21, 0xffffff80, v21
	v_sub_u32_e32 v21, v21, v46
	v_add_u32_e32 v20, 0x6b, v20
	v_add_u32_e32 v21, 0x6a, v21
	s_waitcnt lgkmcnt(0)
	v_not_b32_e32 v24, v22
	v_cmp_gt_i32_e32 vcc, 0, v22
	s_nop 1
	v_cndmask_b32_e64 v22, -|v22|, v24, vcc
	v_and_b32_e32 v22, 0xffffff80, v22
	v_sub_u32_e32 v22, v22, v46
	v_add_u32_e32 v24, 0x69, v22
	v_not_b32_e32 v22, v23
	v_cmp_gt_i32_e32 vcc, 0, v23
	s_nop 1
	v_cndmask_b32_e64 v22, -|v23|, v22, vcc
	v_and_b32_e32 v22, 0xffffff80, v22
	v_sub_u32_e32 v22, v22, v46
	v_add_u32_e32 v25, 0x68, v22
	v_add_u32_e32 v22, 0x4460, v48
	ds_read2_b32 v[22:23], v22 offset1:1
	s_waitcnt lgkmcnt(0)
; DI void phase_topk(const Params& p, int l, int bid, int nblk, char* smem) {
;     ...
;       for (int j = 0; j < 32; ++j) {
;         const u32 u = __float_as_uint(sc[r * 133 + part * 33 + j]);
;         const u32 ord = (u & 0x80000000u) ? ~u : (u | 0x80000000u);
;         key[j] = (ord & ~127u) | (u32)(127 - (part * 32 + j));
;       }
;       float* tv = TV + ((size_t)(row0 + r) * 16 + hh) * 16;
;       int* ti = TI + ((size_t)(row0 + r) * 16 + hh) * 16;
; #pragma unroll
;       for (int k = 2; k <= 32; k <<= 1)
; #pragma unroll
;         for (int j = k >> 1; j > 0; j >>= 1)
; #pragma unroll
;           for (int i = 0; i < 32; ++i) {
;             const int l2 = i ^ j;
;             if (l2 > i) {
;               const u32 ka = key[i], kb2 = key[l2];
;               const u32 lo = ka < kb2 ? ka : kb2, hi = ka < kb2 ? kb2 : ka;
;               if ((i & k) == 0) { key[i] = lo; key[l2] = hi; } else { key[i] = hi; key[l2] = lo; }
;             }
;           }
	v_not_b32_e32 v26, v22
	v_cmp_gt_i32_e32 vcc, 0, v22
	s_nop 1
	v_cndmask_b32_e64 v22, -|v22|, v26, vcc
	v_and_b32_e32 v22, 0xffffff80, v22
	v_sub_u32_e32 v22, v22, v46
	v_add_u32_e32 v26, 0x67, v22
	v_not_b32_e32 v22, v23
	v_cmp_gt_i32_e32 vcc, 0, v23
	s_nop 1
	v_cndmask_b32_e64 v22, -|v23|, v22, vcc
	v_and_b32_e32 v22, 0xffffff80, v22
	v_sub_u32_e32 v22, v22, v46
	v_add_u32_e32 v27, 0x66, v22
	v_add_u32_e32 v22, 0x4468, v48
	ds_read2_b32 v[22:23], v22 offset1:1
	s_waitcnt lgkmcnt(0)
	v_not_b32_e32 v28, v22
	v_cmp_gt_i32_e32 vcc, 0, v22
	s_nop 1
	v_cndmask_b32_e64 v22, -|v22|, v28, vcc
	v_and_b32_e32 v22, 0xffffff80, v22
	v_sub_u32_e32 v22, v22, v46
	v_add_u32_e32 v28, 0x65, v22
	v_not_b32_e32 v22, v23
	v_cmp_gt_i32_e32 vcc, 0, v23
	s_nop 1
	v_cndmask_b32_e64 v22, -|v23|, v22, vcc
	v_and_b32_e32 v22, 0xffffff80, v22
	v_sub_u32_e32 v22, v22, v46
	v_add_u32_e32 v29, 0x64, v22
	v_add_u32_e32 v22, 0x4470, v48
	ds_read2_b32 v[22:23], v22 offset1:1
	s_waitcnt lgkmcnt(0)
	v_not_b32_e32 v30, v22
	v_cmp_gt_i32_e32 vcc, 0, v22
	s_nop 1
	v_cndmask_b32_e64 v22, -|v22|, v30, vcc
	v_and_b32_e32 v22, 0xffffff80, v22
	v_sub_u32_e32 v22, v22, v46
	v_add_u32_e32 v30, 0x63, v22
	v_not_b32_e32 v22, v23
	v_cmp_gt_i32_e32 vcc, 0, v23
	s_nop 1
	v_cndmask_b32_e64 v22, -|v23|, v22, vcc
	v_and_b32_e32 v22, 0xffffff80, v22
	v_sub_u32_e32 v22, v22, v46
	v_add_u32_e32 v31, 0x62, v22
	v_add_u32_e32 v22, 0x4478, v48
	ds_read2_b32 v[22:23], v22 offset1:1
	s_waitcnt lgkmcnt(0)
	v_not_b32_e32 v49, v22
	v_cmp_gt_i32_e32 vcc, 0, v22
	s_nop 1
	v_cndmask_b32_e64 v22, -|v22|, v49, vcc
	v_not_b32_e32 v49, v23
	v_cmp_gt_i32_e32 vcc, 0, v23
	v_and_b32_e32 v22, 0xffffff80, v22
	v_sub_u32_e32 v22, v22, v46
	v_cndmask_b32_e64 v23, -|v23|, v49, vcc
	v_and_b32_e32 v23, 0xffffff80, v23
	v_sub_u32_e32 v23, v23, v46
	v_add_u32_e32 v22, 0x61, v22
	v_add_u32_e32 v23, 0x60, v23
	v_min_u32_e32 v49, v2, v3
	v_max_u32_e32 v2, v2, v3
	v_min_u32_e32 v3, v4, v5
	v_max_u32_e32 v4, v4, v5
	v_min_u32_e32 v5, v6, v7
	v_max_u32_e32 v6, v6, v7
	v_min_u32_e32 v7, v8, v9
	v_max_u32_e32 v8, v8, v9
	v_min_u32_e32 v9, v10, v11
	v_max_u32_e32 v10, v10, v11
	v_min_u32_e32 v11, v12, v13
	v_max_u32_e32 v12, v12, v13
	v_min_u32_e32 v13, v14, v15
	v_max_u32_e32 v14, v14, v15
	v_min_u32_e32 v15, v0, v1
	v_max_u32_e32 v0, v0, v1
	v_min_u32_e32 v1, v16, v17
	v_max_u32_e32 v16, v16, v17
	v_min_u32_e32 v17, v18, v19
	v_max_u32_e32 v18, v18, v19
	v_min_u32_e32 v19, v20, v21
	v_max_u32_e32 v20, v20, v21
	v_min_u32_e32 v21, v24, v25
	v_max_u32_e32 v24, v24, v25
	v_min_u32_e32 v25, v26, v27
	v_max_u32_e32 v26, v26, v27
	v_min_u32_e32 v27, v28, v29
	v_max_u32_e32 v28, v28, v29
	v_min_u32_e32 v29, v30, v31
	v_max_u32_e32 v30, v30, v31
	v_min_u32_e32 v31, v22, v23
	v_max_u32_e32 v22, v22, v23
	v_min_u32_e32 v23, v49, v4
	v_max_u32_e32 v4, v49, v4
	v_min_u32_e32 v49, v2, v3
	v_max_u32_e32 v2, v2, v3
	v_min_u32_e32 v3, v5, v8
	v_max_u32_e32 v5, v5, v8
	v_min_u32_e32 v8, v6, v7
	v_max_u32_e32 v6, v6, v7
	v_min_u32_e32 v7, v9, v12
	v_max_u32_e32 v9, v9, v12
	v_min_u32_e32 v12, v10, v11
	v_max_u32_e32 v10, v10, v11
	v_min_u32_e32 v11, v13, v0
	v_max_u32_e32 v0, v13, v0
	v_min_u32_e32 v13, v14, v15
	v_max_u32_e32 v14, v14, v15
	v_min_u32_e32 v15, v1, v18
	v_max_u32_e32 v1, v1, v18
	v_min_u32_e32 v18, v16, v17
	v_max_u32_e32 v16, v16, v17
	v_min_u32_e32 v17, v19, v24
	v_max_u32_e32 v19, v19, v24
	v_min_u32_e32 v24, v20, v21
	v_max_u32_e32 v20, v20, v21
	v_min_u32_e32 v21, v25, v28
	v_max_u32_e32 v25, v25, v28
	v_min_u32_e32 v28, v26, v27
	v_max_u32_e32 v26, v26, v27
	v_min_u32_e32 v27, v29, v22
	v_max_u32_e32 v22, v29, v22
	v_min_u32_e32 v29, v30, v31
	v_max_u32_e32 v30, v30, v31
	v_min_u32_e32 v31, v23, v49
	v_max_u32_e32 v23, v23, v49
	v_min_u32_e32 v49, v4, v2
	v_max_u32_e32 v2, v4, v2
	v_min_u32_e32 v4, v5, v6
	v_max_u32_e32 v5, v5, v6
	v_min_u32_e32 v6, v3, v8
	v_max_u32_e32 v3, v3, v8
	v_min_u32_e32 v8, v7, v12
	v_max_u32_e32 v7, v7, v12
	v_min_u32_e32 v12, v9, v10
	v_max_u32_e32 v9, v9, v10
	v_min_u32_e32 v10, v0, v14
	v_max_u32_e32 v0, v0, v14
	v_min_u32_e32 v14, v11, v13
	v_max_u32_e32 v11, v11, v13
	v_min_u32_e32 v13, v15, v18
	v_max_u32_e32 v15, v15, v18
	v_min_u32_e32 v18, v1, v16
	v_max_u32_e32 v1, v1, v16
	v_min_u32_e32 v16, v19, v20
	v_max_u32_e32 v19, v19, v20
	v_min_u32_e32 v20, v17, v24
	v_max_u32_e32 v17, v17, v24
	v_min_u32_e32 v24, v21, v28
	v_max_u32_e32 v21, v21, v28
	v_min_u32_e32 v28, v25, v26
	v_max_u32_e32 v25, v25, v26
	v_min_u32_e32 v26, v22, v30
	v_max_u32_e32 v22, v22, v30
	v_min_u32_e32 v30, v27, v29
	v_max_u32_e32 v27, v27, v29
	v_min_u32_e32 v29, v31, v5
	v_max_u32_e32 v5, v31, v5
	v_min_u32_e32 v31, v23, v4
	v_max_u32_e32 v4, v23, v4
	v_min_u32_e32 v23, v49, v3
	v_max_u32_e32 v3, v49, v3
	v_min_u32_e32 v49, v2, v6
	v_max_u32_e32 v2, v2, v6
	v_min_u32_e32 v6, v8, v0
	v_max_u32_e32 v0, v8, v0
	v_min_u32_e32 v8, v7, v10
	v_max_u32_e32 v7, v7, v10
	v_min_u32_e32 v10, v12, v11
	v_max_u32_e32 v11, v12, v11
	v_min_u32_e32 v12, v9, v14
	v_max_u32_e32 v9, v9, v14
	v_min_u32_e32 v14, v13, v19
	v_max_u32_e32 v13, v13, v19
	v_min_u32_e32 v19, v15, v16
	v_max_u32_e32 v15, v15, v16
	v_min_u32_e32 v16, v18, v17
	v_max_u32_e32 v17, v18, v17
	v_min_u32_e32 v18, v1, v20
	v_max_u32_e32 v1, v1, v20
	v_min_u32_e32 v20, v24, v22
	v_max_u32_e32 v22, v24, v22
	v_min_u32_e32 v24, v21, v26
	v_max_u32_e32 v21, v21, v26
	v_min_u32_e32 v26, v28, v27
	v_max_u32_e32 v27, v28, v27
	v_min_u32_e32 v28, v25, v30
	v_max_u32_e32 v25, v25, v30
	v_min_u32_e32 v30, v29, v23
	v_max_u32_e32 v23, v29, v23
	v_min_u32_e32 v29, v31, v49
	v_max_u32_e32 v31, v31, v49
	v_min_u32_e32 v49, v5, v3
	v_max_u32_e32 v3, v5, v3
	v_min_u32_e32 v5, v4, v2
; DI void phase_topk(const Params& p, int l, int bid, int nblk, char* smem) {
;     ...
; #pragma unroll
;       for (int k = 2; k <= 32; k <<= 1)
; #pragma unroll
;         for (int j = k >> 1; j > 0; j >>= 1)
; #pragma unroll
;           for (int i = 0; i < 32; ++i) {
;             const int l2 = i ^ j;
;             if (l2 > i) {
;               const u32 ka = key[i], kb2 = key[l2];
;               const u32 lo = ka < kb2 ? ka : kb2, hi = ka < kb2 ? kb2 : ka;
;               if ((i & k) == 0) { key[i] = lo; key[l2] = hi; } else { key[i] = hi; key[l2] = lo; }
;             }
;           }
	v_max_u32_e32 v2, v4, v2
	v_min_u32_e32 v4, v0, v11
	v_max_u32_e32 v0, v0, v11
	v_min_u32_e32 v11, v7, v9
	v_max_u32_e32 v7, v7, v9
	v_min_u32_e32 v9, v6, v10
	v_max_u32_e32 v6, v6, v10
	v_min_u32_e32 v10, v8, v12
	v_max_u32_e32 v8, v8, v12
	v_min_u32_e32 v12, v14, v16
	v_max_u32_e32 v14, v14, v16
	v_min_u32_e32 v16, v19, v18
	v_max_u32_e32 v18, v19, v18
	v_min_u32_e32 v19, v13, v17
	v_max_u32_e32 v13, v13, v17
	v_min_u32_e32 v17, v15, v1
	v_max_u32_e32 v1, v15, v1
	v_min_u32_e32 v15, v22, v27
	v_max_u32_e32 v22, v22, v27
	v_min_u32_e32 v27, v21, v25
	v_max_u32_e32 v21, v21, v25
	v_min_u32_e32 v25, v20, v26
	v_max_u32_e32 v20, v20, v26
	v_min_u32_e32 v26, v24, v28
	v_max_u32_e32 v24, v24, v28
	v_min_u32_e32 v28, v30, v29
	v_max_u32_e32 v29, v30, v29
	v_min_u32_e32 v30, v23, v31
	v_max_u32_e32 v23, v23, v31
	v_min_u32_e32 v31, v49, v5
	v_max_u32_e32 v5, v49, v5
	v_min_u32_e32 v49, v3, v2
	v_max_u32_e32 v2, v3, v2
	v_min_u32_e32 v3, v0, v7
	v_max_u32_e32 v0, v0, v7
	v_min_u32_e32 v7, v4, v11
	v_max_u32_e32 v4, v4, v11
	v_min_u32_e32 v11, v6, v8
	v_max_u32_e32 v6, v6, v8
	v_min_u32_e32 v8, v9, v10
	v_max_u32_e32 v9, v9, v10
	v_min_u32_e32 v10, v12, v16
	v_max_u32_e32 v12, v12, v16
	v_min_u32_e32 v16, v14, v18
	v_max_u32_e32 v14, v14, v18
	v_min_u32_e32 v18, v19, v17
	v_max_u32_e32 v17, v19, v17
	v_min_u32_e32 v19, v13, v1
	v_max_u32_e32 v1, v13, v1
	v_min_u32_e32 v13, v22, v21
	v_max_u32_e32 v21, v22, v21
	v_min_u32_e32 v22, v15, v27
	v_max_u32_e32 v15, v15, v27
	v_min_u32_e32 v27, v20, v24
	v_max_u32_e32 v20, v20, v24
	v_min_u32_e32 v24, v25, v26
	v_max_u32_e32 v25, v25, v26
	v_min_u32_e32 v26, v28, v0
	v_max_u32_e32 v0, v28, v0
	v_min_u32_e32 v28, v29, v3
	v_max_u32_e32 v3, v29, v3
	v_min_u32_e32 v29, v30, v4
	v_max_u32_e32 v4, v30, v4
	v_min_u32_e32 v30, v23, v7
	v_max_u32_e32 v7, v23, v7
	v_min_u32_e32 v23, v31, v6
	v_max_u32_e32 v6, v31, v6
	v_min_u32_e32 v31, v5, v11
	v_max_u32_e32 v5, v5, v11
	v_min_u32_e32 v11, v49, v9
	v_max_u32_e32 v9, v49, v9
	v_min_u32_e32 v49, v2, v8
	v_max_u32_e32 v2, v2, v8
	v_min_u32_e32 v8, v10, v21
	v_max_u32_e32 v10, v10, v21
	v_min_u32_e32 v21, v12, v13
	v_max_u32_e32 v12, v12, v13
	v_min_u32_e32 v13, v16, v15
	v_max_u32_e32 v15, v16, v15
	v_min_u32_e32 v16, v14, v22
	v_max_u32_e32 v14, v14, v22
	v_min_u32_e32 v22, v18, v20
	v_max_u32_e32 v18, v18, v20
	v_min_u32_e32 v20, v17, v27
	v_max_u32_e32 v17, v17, v27
	v_min_u32_e32 v27, v19, v25
	v_max_u32_e32 v19, v19, v25
	v_min_u32_e32 v25, v1, v24
	v_max_u32_e32 v1, v1, v24
	v_min_u32_e32 v24, v26, v23
	v_max_u32_e32 v23, v26, v23
	v_min_u32_e32 v26, v28, v31
	v_max_u32_e32 v28, v28, v31
	v_min_u32_e32 v31, v29, v11
	v_max_u32_e32 v11, v29, v11
	v_min_u32_e32 v29, v30, v49
	v_max_u32_e32 v30, v30, v49
	v_min_u32_e32 v49, v0, v6
	v_max_u32_e32 v0, v0, v6
	v_min_u32_e32 v6, v3, v5
	v_max_u32_e32 v3, v3, v5
	v_min_u32_e32 v5, v4, v9
	v_max_u32_e32 v4, v4, v9
	v_min_u32_e32 v9, v7, v2
	v_max_u32_e32 v2, v7, v2
	v_min_u32_e32 v7, v10, v18
	v_max_u32_e32 v10, v10, v18
	v_min_u32_e32 v18, v12, v17
	v_max_u32_e32 v12, v12, v17
	v_min_u32_e32 v17, v15, v19
	v_max_u32_e32 v15, v15, v19
	v_min_u32_e32 v19, v14, v1
	v_max_u32_e32 v1, v14, v1
	v_min_u32_e32 v14, v8, v22
	v_max_u32_e32 v8, v8, v22
	v_min_u32_e32 v22, v21, v20
	v_max_u32_e32 v20, v21, v20
	v_min_u32_e32 v21, v13, v27
	v_max_u32_e32 v13, v13, v27
	v_min_u32_e32 v27, v16, v25
	v_max_u32_e32 v16, v16, v25
	v_min_u32_e32 v25, v24, v31
	v_max_u32_e32 v24, v24, v31
	v_min_u32_e32 v31, v26, v29
	v_max_u32_e32 v26, v26, v29
	v_min_u32_e32 v29, v23, v11
	v_max_u32_e32 v11, v23, v11
	v_min_u32_e32 v23, v28, v30
	v_max_u32_e32 v28, v28, v30
	v_min_u32_e32 v30, v49, v5
	v_max_u32_e32 v5, v49, v5
	v_min_u32_e32 v49, v6, v9
	v_max_u32_e32 v6, v6, v9
	v_min_u32_e32 v9, v0, v4
	v_max_u32_e32 v0, v0, v4
	v_min_u32_e32 v4, v3, v2
	v_max_u32_e32 v2, v3, v2
	v_min_u32_e32 v3, v10, v15
	v_max_u32_e32 v10, v10, v15
	v_min_u32_e32 v15, v12, v1
	v_max_u32_e32 v1, v12, v1
	v_min_u32_e32 v12, v7, v17
	v_max_u32_e32 v7, v7, v17
	v_min_u32_e32 v17, v18, v19
	v_max_u32_e32 v18, v18, v19
	v_min_u32_e32 v19, v8, v13
	v_max_u32_e32 v8, v8, v13
	v_min_u32_e32 v13, v20, v16
	v_max_u32_e32 v16, v20, v16
	v_min_u32_e32 v20, v14, v21
	v_max_u32_e32 v14, v14, v21
	v_min_u32_e32 v21, v22, v27
	v_max_u32_e32 v22, v22, v27
	v_min_u32_e32 v27, v25, v31
	v_min_u32_e32 v50, v24, v26
	v_min_u32_e32 v51, v29, v23
	v_min_u32_e32 v52, v11, v28
	v_min_u32_e32 v53, v30, v49
	v_min_u32_e32 v54, v5, v6
	v_min_u32_e32 v55, v9, v4
	v_min_u32_e32 v56, v0, v2
	v_min_u32_e32 v57, v10, v1
	v_min_u32_e32 v58, v3, v15
	v_min_u32_e32 v59, v7, v18
	v_min_u32_e32 v60, v12, v17
	v_min_u32_e32 v61, v8, v16
	v_min_u32_e32 v62, v19, v13
	v_min_u32_e32 v63, v14, v22
	v_min_u32_e32 v64, v20, v21
	v_max3_u32 v1, v27, v10, v1
	v_max3_u32 v10, v25, v31, v57
	v_max3_u32 v3, v50, v3, v15
	v_max3_u32 v15, v24, v26, v58
	v_max3_u32 v7, v51, v7, v18
	v_max3_u32 v18, v29, v23, v59
	v_max3_u32 v12, v52, v12, v17
	v_max3_u32 v11, v11, v28, v60
	v_max3_u32 v8, v53, v8, v16
	v_max3_u32 v16, v30, v49, v61
	v_max3_u32 v13, v54, v19, v13
	v_max3_u32 v5, v5, v6, v62
	v_max3_u32 v6, v55, v14, v22
	v_max3_u32 v4, v9, v4, v63
	v_max3_u32 v9, v56, v20, v21
	v_max3_u32 v0, v0, v2, v64
	v_min_u32_e32 v2, v1, v8
	v_max_u32_e32 v1, v1, v8
	v_min_u32_e32 v8, v10, v16
	v_max_u32_e32 v10, v10, v16
	v_min_u32_e32 v14, v3, v13
	v_max_u32_e32 v3, v3, v13
	v_min_u32_e32 v13, v15, v5
	v_max_u32_e32 v5, v15, v5
	v_min_u32_e32 v15, v7, v6
	v_max_u32_e32 v6, v7, v6
	v_min_u32_e32 v7, v18, v4
	v_min_u32_e32 v16, v12, v9
	v_max_u32_e32 v9, v12, v9
	v_min_u32_e32 v12, v11, v0
	v_max_u32_e32 v4, v18, v4
; DI void phase_topk(const Params& p, int l, int bid, int nblk, char* smem) {
;     ...
;       u32 T[16];
; #pragma unroll
;       for (int t = 0; t < 16; ++t) T[t] = key[31 - t];
;     ...
;       TOPK_MERGE(DPP_XOR1)
;       TOPK_MERGE(DPP_XOR2)
	v_max_u32_e32 v0, v11, v0
	v_min_u32_e32 v11, v2, v15
	v_max_u32_e32 v2, v2, v15
	v_min_u32_e32 v15, v8, v7
	v_max_u32_e32 v7, v8, v7
	v_min_u32_e32 v8, v14, v16
	v_max_u32_e32 v14, v14, v16
	v_min_u32_e32 v16, v13, v12
	v_max_u32_e32 v12, v13, v12
	v_min_u32_e32 v13, v1, v6
	v_max_u32_e32 v1, v1, v6
	v_min_u32_e32 v6, v10, v4
	v_max_u32_e32 v4, v10, v4
	v_min_u32_e32 v10, v3, v9
	v_max_u32_e32 v3, v3, v9
	v_min_u32_e32 v9, v5, v0
	v_max_u32_e32 v0, v5, v0
	v_min_u32_e32 v5, v11, v8
	v_max_u32_e32 v8, v11, v8
	v_min_u32_e32 v11, v15, v16
	v_max_u32_e32 v15, v15, v16
	v_min_u32_e32 v16, v2, v14
	v_max_u32_e32 v2, v2, v14
	v_min_u32_e32 v14, v7, v12
	v_max_u32_e32 v7, v7, v12
	v_min_u32_e32 v12, v13, v10
	v_max_u32_e32 v10, v13, v10
	v_min_u32_e32 v13, v6, v9
	v_max_u32_e32 v6, v6, v9
	v_min_u32_e32 v9, v1, v3
	v_max_u32_e32 v1, v1, v3
	v_min_u32_e32 v3, v4, v0
	v_max_u32_e32 v0, v4, v0
	v_min_u32_e32 v4, v5, v11
	v_max_u32_e32 v5, v5, v11
	v_min_u32_e32 v11, v8, v15
	v_max_u32_e32 v8, v8, v15
	v_min_u32_e32 v15, v16, v14
	v_max_u32_e32 v14, v16, v14
	v_min_u32_e32 v16, v2, v7
	v_max_u32_e32 v2, v2, v7
	v_min_u32_e32 v7, v12, v13
	v_max_u32_e32 v12, v12, v13
	v_min_u32_e32 v13, v10, v6
	v_max_u32_e32 v6, v10, v6
	v_min_u32_e32 v10, v9, v3
	v_max_u32_e32 v3, v9, v3
	v_min_u32_e32 v9, v1, v0
	v_max_u32_e32 v0, v1, v0
	v_mov_b32_dpp v1, v4 quad_perm:[1,0,3,2] row_mask:0xf bank_mask:0xf bound_ctrl:1
	v_max_u32_dpp v17, v5, v9 quad_perm:[1,0,3,2] row_mask:0xf bank_mask:0xf bound_ctrl:1
	v_max_u32_dpp v18, v11, v3 quad_perm:[1,0,3,2] row_mask:0xf bank_mask:0xf bound_ctrl:1
	v_max_u32_dpp v19, v8, v10 quad_perm:[1,0,3,2] row_mask:0xf bank_mask:0xf bound_ctrl:1
	v_max_u32_dpp v20, v15, v6 quad_perm:[1,0,3,2] row_mask:0xf bank_mask:0xf bound_ctrl:1
	v_max_u32_dpp v21, v14, v13 quad_perm:[1,0,3,2] row_mask:0xf bank_mask:0xf bound_ctrl:1
	v_max_u32_dpp v22, v16, v12 quad_perm:[1,0,3,2] row_mask:0xf bank_mask:0xf bound_ctrl:1
	v_max_u32_dpp v23, v2, v7 quad_perm:[1,0,3,2] row_mask:0xf bank_mask:0xf bound_ctrl:1
	v_max_u32_dpp v12, v12, v16 quad_perm:[1,0,3,2] row_mask:0xf bank_mask:0xf bound_ctrl:1
	v_max_u32_dpp v13, v13, v14 quad_perm:[1,0,3,2] row_mask:0xf bank_mask:0xf bound_ctrl:1
	v_max_u32_dpp v6, v6, v15 quad_perm:[1,0,3,2] row_mask:0xf bank_mask:0xf bound_ctrl:1
	v_max_u32_dpp v8, v10, v8 quad_perm:[1,0,3,2] row_mask:0xf bank_mask:0xf bound_ctrl:1
	v_max_u32_dpp v3, v3, v11 quad_perm:[1,0,3,2] row_mask:0xf bank_mask:0xf bound_ctrl:1
	v_max_u32_dpp v5, v9, v5 quad_perm:[1,0,3,2] row_mask:0xf bank_mask:0xf bound_ctrl:1
	v_max_u32_dpp v4, v0, v4 quad_perm:[1,0,3,2] row_mask:0xf bank_mask:0xf bound_ctrl:1
	v_max_u32_dpp v2, v7, v2 quad_perm:[1,0,3,2] row_mask:0xf bank_mask:0xf bound_ctrl:1
	v_max_u32_e32 v0, v0, v1
	v_max_u32_e32 v1, v0, v2
	v_min_u32_e32 v0, v0, v2
	v_max_u32_e32 v2, v17, v12
	v_min_u32_e32 v7, v17, v12
	v_max_u32_e32 v9, v18, v13
	v_min_u32_e32 v10, v18, v13
	v_max_u32_e32 v11, v19, v6
	v_min_u32_e32 v6, v19, v6
	v_max_u32_e32 v12, v20, v8
	v_min_u32_e32 v8, v20, v8
	v_max_u32_e32 v13, v21, v3
	v_min_u32_e32 v3, v21, v3
	v_max_u32_e32 v14, v22, v5
	v_min_u32_e32 v5, v22, v5
	v_max_u32_e32 v15, v23, v4
	v_min_u32_e32 v4, v23, v4
	v_max_u32_e32 v16, v1, v12
	v_min_u32_e32 v1, v1, v12
	v_max_u32_e32 v12, v2, v13
	v_min_u32_e32 v2, v2, v13
	v_max_u32_e32 v13, v9, v14
	v_min_u32_e32 v9, v9, v14
	v_max_u32_e32 v14, v11, v15
	v_min_u32_e32 v11, v11, v15
	v_max_u32_e32 v15, v0, v8
	v_min_u32_e32 v0, v0, v8
	v_max_u32_e32 v8, v7, v3
	v_min_u32_e32 v3, v7, v3
	v_max_u32_e32 v7, v10, v5
	v_min_u32_e32 v5, v10, v5
	v_max_u32_e32 v10, v6, v4
	v_min_u32_e32 v4, v6, v4
	v_max_u32_e32 v6, v16, v13
	v_min_u32_e32 v13, v16, v13
	v_max_u32_e32 v16, v12, v14
	v_min_u32_e32 v14, v12, v14
	v_max_u32_e32 v17, v1, v9
	v_min_u32_e32 v1, v1, v9
	v_max_u32_e32 v9, v2, v11
	v_min_u32_e32 v11, v2, v11
	v_max_u32_e32 v18, v15, v7
	v_min_u32_e32 v7, v15, v7
	v_max_u32_e32 v15, v8, v10
	v_min_u32_e32 v10, v8, v10
	v_max_u32_e32 v19, v0, v5
	v_min_u32_e32 v5, v0, v5
	v_max_u32_e32 v22, v3, v4
	v_min_u32_e32 v23, v3, v4
	v_max_u32_e32 v12, v6, v16
	v_min_u32_e32 v2, v6, v16
	v_max_u32_e32 v8, v13, v14
	v_min_u32_e32 v0, v13, v14
	v_max_u32_e32 v13, v17, v9
	v_min_u32_e32 v3, v17, v9
	v_max_u32_e32 v9, v1, v11
	v_min_u32_e32 v1, v1, v11
	v_max_u32_e32 v20, v18, v15
	v_min_u32_e32 v6, v18, v15
	v_max_u32_e32 v14, v7, v10
	v_min_u32_e32 v4, v7, v10
	v_max_u32_e32 v21, v19, v22
	v_min_u32_e32 v7, v19, v22
	v_max_u32_e32 v16, v5, v23
	v_min_u32_e32 v5, v5, v23
	v_mov_b32_dpp v24, v7 quad_perm:[2,3,0,1] row_mask:0xf bank_mask:0xf bound_ctrl:1
	v_mov_b32_dpp v15, v16 quad_perm:[2,3,0,1] row_mask:0xf bank_mask:0xf bound_ctrl:1
	v_mov_b32_dpp v26, v5 quad_perm:[2,3,0,1] row_mask:0xf bank_mask:0xf bound_ctrl:1
	v_mov_b32_dpp v10, v21 quad_perm:[2,3,0,1] row_mask:0xf bank_mask:0xf bound_ctrl:1
	v_mov_b32_dpp v27, v4 quad_perm:[2,3,0,1] row_mask:0xf bank_mask:0xf bound_ctrl:1
	v_mov_b32_dpp v17, v14 quad_perm:[2,3,0,1] row_mask:0xf bank_mask:0xf bound_ctrl:1
	v_mov_b32_dpp v25, v6 quad_perm:[2,3,0,1] row_mask:0xf bank_mask:0xf bound_ctrl:1
	v_mov_b32_dpp v11, v20 quad_perm:[2,3,0,1] row_mask:0xf bank_mask:0xf bound_ctrl:1
	v_mov_b32_dpp v30, v1 quad_perm:[2,3,0,1] row_mask:0xf bank_mask:0xf bound_ctrl:1
	v_mov_b32_dpp v22, v9 quad_perm:[2,3,0,1] row_mask:0xf bank_mask:0xf bound_ctrl:1
	v_mov_b32_dpp v28, v3 quad_perm:[2,3,0,1] row_mask:0xf bank_mask:0xf bound_ctrl:1
	v_mov_b32_dpp v18, v13 quad_perm:[2,3,0,1] row_mask:0xf bank_mask:0xf bound_ctrl:1
	v_mov_b32_dpp v31, v0 quad_perm:[2,3,0,1] row_mask:0xf bank_mask:0xf bound_ctrl:1
; DI void phase_topk(const Params& p, int l, int bid, int nblk, char* smem) {
;     ...
;       TOPK_MERGE(DPP_XOR1)
;       TOPK_MERGE(DPP_XOR2)
;     ...
;       if (part == 0) {
;         float ov[16];
;         int oi[16];
; #pragma unroll
;         for (int rd = 0; rd < 16; ++rd) {
;           const u32 best = T[rd];
;           const u32 ordv = best & ~127u;
;           const u32 uu = (ordv & 0x80000000u) ? (ordv & 0x7FFFFFFFu) : ~ordv;
;           ov[rd] = __uint_as_float(uu);
;           oi[rd] = 127 - (int)(best & 127u);
;         }
; #pragma unroll
;         for (int q = 0; q < 4; ++q) {
;           float4 fv = {ov[q * 4 + 0], ov[q * 4 + 1], ov[q * 4 + 2], ov[q * 4 + 3]};
;           int4 iv = {oi[q * 4 + 0], oi[q * 4 + 1], oi[q * 4 + 2], oi[q * 4 + 3]};
;           *(float4*)(tv + q * 4) = fv;
;           *(int4*)(ti + q * 4) = iv;
;         }
;       }
	v_mov_b32_dpp v23, v8 quad_perm:[2,3,0,1] row_mask:0xf bank_mask:0xf bound_ctrl:1
	v_mov_b32_dpp v29, v2 quad_perm:[2,3,0,1] row_mask:0xf bank_mask:0xf bound_ctrl:1
	v_mov_b32_dpp v19, v12 quad_perm:[2,3,0,1] row_mask:0xf bank_mask:0xf bound_ctrl:1
	s_and_saveexec_b64 s[34:35], s[0:1]
	v_max_u32_e32 v12, v12, v26
	v_max_u32_e32 v20, v20, v30
	v_max_u32_e32 v13, v13, v27
	v_max_u32_e32 v21, v21, v31
	v_max_u32_e32 v8, v8, v24
	v_max_u32_e32 v14, v14, v28
	v_max_u32_e32 v9, v9, v25
	v_max_u32_e32 v16, v16, v29
	v_max_u32_e32 v2, v2, v15
	v_max_u32_e32 v6, v6, v22
	v_max_u32_e32 v3, v3, v17
	v_max_u32_e32 v7, v7, v23
	v_max_u32_e32 v0, v0, v10
	v_max_u32_e32 v4, v4, v18
	v_max_u32_e32 v1, v1, v11
	v_max_u32_e32 v5, v5, v19
	v_min_u32_e32 v26, v12, v20
	v_min_u32_e32 v27, v13, v21
	v_min_u32_e32 v24, v8, v14
	v_min_u32_e32 v25, v9, v16
	v_min_u32_e32 v15, v2, v6
	v_min_u32_e32 v17, v3, v7
	v_min_u32_e32 v10, v0, v4
	v_min_u32_e32 v11, v1, v5
	v_max_u32_e32 v12, v12, v20
	v_max_u32_e32 v13, v13, v21
	v_max_u32_e32 v8, v8, v14
	v_max_u32_e32 v9, v9, v16
	v_max_u32_e32 v2, v2, v6
	v_max_u32_e32 v3, v3, v7
	v_max_u32_e32 v0, v0, v4
	v_max_u32_e32 v1, v1, v5
	v_min_u32_e32 v20, v12, v13
	v_min_u32_e32 v14, v8, v9
	v_min_u32_e32 v6, v2, v3
	v_min_u32_e32 v4, v0, v1
	v_min_u32_e32 v16, v20, v14
	v_min_u32_e32 v5, v6, v4
	v_min_u32_e32 v21, v16, v5
	v_max_u32_e32 v16, v16, v5
	v_max_u32_e32 v5, v20, v14
	v_max_u32_e32 v4, v6, v4
	v_min_u32_e32 v14, v5, v4
	v_max_u32_e32 v20, v5, v4
	v_max_u32_e32 v4, v12, v13
	v_max_u32_e32 v5, v8, v9
	v_max_u32_e32 v2, v2, v3
	v_max_u32_e32 v0, v0, v1
	v_min_u32_e32 v6, v4, v5
	v_min_u32_e32 v1, v2, v0
	v_min_u32_e32 v3, v6, v1
	v_max_u32_e32 v8, v6, v1
	v_max_u32_e32 v1, v4, v5
	v_max_u32_e32 v0, v2, v0
	v_min_u32_e32 v2, v1, v0
	v_max_u32_e32 v9, v1, v0
	v_add_u32_e32 v0, s40, v45
	v_ashrrev_i32_e32 v1, 31, v0
	v_lshlrev_b64 v[0:1], 10, v[0:1]
	v_readlane_b32 s16, v255, 50
	v_min_u32_e32 v30, v26, v27
	v_min_u32_e32 v28, v24, v25
	v_min_u32_e32 v22, v15, v17
	v_min_u32_e32 v18, v10, v11
	v_max_u32_e32 v26, v26, v27
	v_max_u32_e32 v24, v24, v25
	v_max_u32_e32 v15, v15, v17
	v_max_u32_e32 v10, v10, v11
	v_lshl_or_b32 v0, s39, 6, v0
	v_readlane_b32 s17, v255, 51
	v_min_u32_e32 v25, v26, v24
	v_min_u32_e32 v11, v15, v10
	v_max_u32_e32 v24, v26, v24
	v_max_u32_e32 v10, v15, v10
	v_lshl_add_u64 v[4:5], s[68:69], 0, v[0:1]
	v_lshl_add_u64 v[6:7], s[16:17], 0, v[0:1]
	v_and_b32_e32 v0, 0xffffff80, v2
	v_min_u32_e32 v15, v24, v10
	v_max_u32_e32 v10, v24, v10
	v_and_b32_e32 v1, 0xffffff80, v9
	v_and_b32_e32 v24, 0x7fffff80, v2
	v_xor_b32_e32 v0, -1, v0
	v_cmp_gt_i32_e32 vcc, 0, v2
	v_min_u32_e32 v17, v25, v11
	v_max_u32_e32 v11, v25, v11
	v_xor_b32_e32 v12, -1, v2
	v_and_b32_e32 v25, 0x7fffff80, v9
	v_xor_b32_e32 v26, -1, v1
	v_cndmask_b32_e32 v1, v0, v24, vcc
	v_cmp_gt_i32_e32 vcc, 0, v9
	v_and_b32_e32 v2, 0xffffff80, v3
	v_xor_b32_e32 v2, -1, v2
	v_cndmask_b32_e32 v0, v26, v25, vcc
	v_and_b32_e32 v25, 0xffffff80, v8
	v_and_b32_e32 v26, 0x7fffff80, v3
	v_cmp_gt_i32_e32 vcc, 0, v3
	v_xor_b32_e32 v13, -1, v9
	v_xor_b32_e32 v9, -1, v3
	v_and_b32_e32 v27, 0x7fffff80, v8
	v_xor_b32_e32 v25, -1, v25
	v_cndmask_b32_e32 v3, v2, v26, vcc
	v_cmp_gt_i32_e32 vcc, 0, v8
	v_xor_b32_e32 v24, -1, v8
	v_xor_b32_e32 v8, -1, v14
	v_cndmask_b32_e32 v2, v25, v27, vcc
	global_store_dwordx4 v[4:5], v[0:3], off
	v_cmp_gt_i32_e32 vcc, 0, v14
	v_min_u32_e32 v29, v30, v28
	v_and_b32_e32 v1, 0x7f, v12
	v_and_b32_e32 v0, 0x7f, v13
	v_and_b32_e32 v3, 0x7f, v9
	v_and_b32_e32 v2, 0x7f, v24
	global_store_dwordx4 v[6:7], v[0:3], off
	v_xor_b32_e32 v9, -1, v20
	v_xor_b32_e32 v13, -1, v16
	v_and_b32_e32 v0, 0xffffff80, v14
	v_and_b32_e32 v1, 0xffffff80, v20
	v_and_b32_e32 v2, 0x7fffff80, v14
	v_xor_b32_e32 v0, -1, v0
	v_and_b32_e32 v3, 0x7fffff80, v20
	v_xor_b32_e32 v12, -1, v1
	v_cndmask_b32_e32 v1, v0, v2, vcc
	v_cmp_gt_i32_e32 vcc, 0, v20
	v_and_b32_e32 v2, 0xffffff80, v21
	v_and_b32_e32 v14, 0x7fffff80, v21
	v_cndmask_b32_e32 v0, v12, v3, vcc
	v_and_b32_e32 v3, 0xffffff80, v16
	v_xor_b32_e32 v2, -1, v2
	v_cmp_gt_i32_e32 vcc, 0, v21
	v_and_b32_e32 v20, 0x7fffff80, v16
	v_xor_b32_e32 v24, -1, v3
	v_cndmask_b32_e32 v3, v2, v14, vcc
	v_cmp_gt_i32_e32 vcc, 0, v16
	v_xor_b32_e32 v12, -1, v21
	v_and_b32_e32 v14, 0x7fffff80, v11
	v_cndmask_b32_e32 v2, v24, v20, vcc
	global_store_dwordx4 v[4:5], v[0:3], off offset:16
	v_cmp_gt_i32_e32 vcc, 0, v15
	v_min_u32_e32 v19, v22, v18
	v_and_b32_e32 v1, 0x7f, v8
	v_and_b32_e32 v0, 0x7f, v9
	v_and_b32_e32 v3, 0x7f, v12
	v_and_b32_e32 v2, 0x7f, v13
	global_store_dwordx4 v[6:7], v[0:3], off offset:16
	v_and_b32_e32 v13, 0x7fffff80, v17
	v_xor_b32_e32 v8, -1, v15
	v_and_b32_e32 v0, 0xffffff80, v15
	v_and_b32_e32 v1, 0xffffff80, v10
	v_and_b32_e32 v2, 0x7fffff80, v15
	v_xor_b32_e32 v0, -1, v0
	v_and_b32_e32 v3, 0x7fffff80, v10
	v_xor_b32_e32 v12, -1, v1
	v_cndmask_b32_e32 v1, v0, v2, vcc
	v_cmp_gt_i32_e32 vcc, 0, v10
	v_and_b32_e32 v2, 0xffffff80, v17
	v_xor_b32_e32 v2, -1, v2
	v_cndmask_b32_e32 v0, v12, v3, vcc
	v_and_b32_e32 v3, 0xffffff80, v11
	v_cmp_gt_i32_e32 vcc, 0, v17
	v_xor_b32_e32 v15, -1, v3
	v_max_u32_e32 v28, v30, v28
	v_cndmask_b32_e32 v3, v2, v13, vcc
	v_cmp_gt_i32_e32 vcc, 0, v11
	v_max_u32_e32 v18, v22, v18
	v_xor_b32_e32 v9, -1, v10
	v_xor_b32_e32 v10, -1, v17
	v_xor_b32_e32 v12, -1, v11
	v_cndmask_b32_e32 v2, v15, v14, vcc
	v_min_u32_e32 v22, v28, v18
	global_store_dwordx4 v[4:5], v[0:3], off offset:32
	v_max_u32_e32 v18, v28, v18
	v_min_u32_e32 v23, v29, v19
	v_and_b32_e32 v1, 0x7f, v8
	v_and_b32_e32 v0, 0x7f, v9
	v_and_b32_e32 v3, 0x7f, v10
	v_and_b32_e32 v2, 0x7f, v12
	global_store_dwordx4 v[6:7], v[0:3], off offset:32
	v_cmp_gt_i32_e32 vcc, 0, v22
	v_max_u32_e32 v19, v29, v19
	v_and_b32_e32 v0, 0xffffff80, v22
	v_and_b32_e32 v1, 0xffffff80, v18
	v_and_b32_e32 v2, 0x7fffff80, v22
	v_xor_b32_e32 v0, -1, v0
	v_and_b32_e32 v3, 0x7fffff80, v18
	v_xor_b32_e32 v10, -1, v1
	v_cndmask_b32_e32 v1, v0, v2, vcc
	v_cmp_gt_i32_e32 vcc, 0, v18
	v_and_b32_e32 v2, 0xffffff80, v23
	v_and_b32_e32 v12, 0x7fffff80, v23
	v_cndmask_b32_e32 v0, v10, v3, vcc
	v_and_b32_e32 v3, 0xffffff80, v19
	v_xor_b32_e32 v2, -1, v2
	v_cmp_gt_i32_e32 vcc, 0, v23
	v_and_b32_e32 v13, 0x7fffff80, v19
	v_xor_b32_e32 v14, -1, v3
	v_cndmask_b32_e32 v3, v2, v12, vcc
	v_cmp_gt_i32_e32 vcc, 0, v19
	v_xor_b32_e32 v8, -1, v22
	v_xor_b32_e32 v9, -1, v18
	v_xor_b32_e32 v10, -1, v23
	v_xor_b32_e32 v11, -1, v19
	v_cndmask_b32_e32 v2, v14, v13, vcc
	global_store_dwordx4 v[4:5], v[0:3], off offset:48
	s_nop 1
	v_and_b32_e32 v1, 0x7f, v8
	v_and_b32_e32 v0, 0x7f, v9
	v_and_b32_e32 v3, 0x7f, v10
	v_and_b32_e32 v2, 0x7f, v11
	global_store_dwordx4 v[6:7], v[0:3], off offset:48
	s_branch .LBB0_1447
